# E5 combine loop fully unrolled with per-iteration register banks, 24 loads in flight (on v5)
# baseline (speedup 1.0000x reference)
; __device__ __forceinline__ unsigned cvt_pk_bf16(float lo, float hi) { unsigned r; asm volatile("v_cvt_pk_bf16_f32 %0, %1, %2" : "=v"(r) : "v"(lo), "v"(hi)); return r; }
; __device__ __forceinline__ float bf2f(unsigned h) { return __uint_as_float(h << 16); }
; #define LSE ((float*)WSP(WS_A + A_LSE))
; __global__ void __launch_bounds__(512, 2) mega_fwd(KArgs a) {
;     ...
;             for (int e = gw * 64 + lane; e < T_ * 32; e += NGW * 64) {
;                 const int t = e >> 5, h = (e >> 3) & 3, ch = e & 7;
;                 const float l0 = LSE[(size_t)t * 12 + h], l1 = LSE[(size_t)t * 12 + 4 + h], l2 = LSE[(size_t)t * 12 + 8 + h];
;                 const u32x4 a0 = *(const u32x4*)(ODIL + ((size_t)t * 12 + h) * 64 + ch * 8), a1 = *(const u32x4*)(ODIL + ((size_t)t * 12 + 4 + h) * 64 + ch * 8), a2 = *(const u32x4*)(ODIL + ((size_t)t * 12 + 8 + h) * 64 + ch * 8);
;                 const float mx = fmaxf(l0, fmaxf(l1, l2));
;                 float w0 = __builtin_amdgcn_exp2f(l0 - mx), w1 = __builtin_amdgcn_exp2f(l1 - mx), w2 = __builtin_amdgcn_exp2f(l2 - mx);
;                 const float inv = __builtin_amdgcn_rcpf(w0 + w1 + w2); w0 *= inv; w1 *= inv; w2 *= inv;
;                 u32x4 o;
; #pragma unroll
;                 for (int q = 0; q < 4; ++q) {
;                     const float lo = w0 * bf2f(a0[q] & 0xffffu) + w1 * bf2f(a1[q] & 0xffffu) + w2 * bf2f(a2[q] & 0xffffu);
;                     const float hi2 = w0 * bf2f(a0[q] >> 16) + w1 * bf2f(a1[q] >> 16) + w2 * bf2f(a2[q] >> 16);
;                     o[q] = pg8::cvt_pk_bf16(lo, hi2);
;                 }
;                 *(u32x4*)(MIX + (size_t)t * 768 + 512 + h * 64 + ch * 8) = o;
;             }
.LBB0_4405:
	v_ashrrev_i32_e32 v9, 5, v1
	v_bfe_u32 v10, v1, 3, 2
	v_mad_i64_i32 v[2:3], s[10:11], v9, 12, 0
	v_or_b32_e32 v2, v2, v10
	v_lshl_add_u64 v[4:5], v[2:3], 2, s[4:5]
	v_lshl_add_u64 v[12:13], v[2:3], 0, 4
	global_load_dword v11, v[4:5], off
	v_lshl_add_u64 v[4:5], v[12:13], 2, s[4:5]
	v_lshl_add_u64 v[16:17], v[2:3], 0, 8
	global_load_dword v20, v[4:5], off
	v_lshl_add_u64 v[4:5], v[16:17], 2, s[4:5]
	global_load_dword v22, v[4:5], off
	v_lshlrev_b64 v[2:3], 7, v[2:3]
	v_and_b32_e32 v4, 56, v8
	v_lshlrev_b64 v[12:13], 7, v[12:13]
	v_lshl_add_u64 v[2:3], s[6:7], 0, v[2:3]
	v_lshlrev_b32_e32 v6, 1, v4
	v_mov_b32_e32 v7, v0
	v_lshl_add_u64 v[12:13], s[6:7], 0, v[12:13]
	v_lshlrev_b64 v[16:17], 7, v[16:17]
	v_lshl_add_u64 v[2:3], v[2:3], 0, v[6:7]
	v_lshl_add_u64 v[12:13], v[12:13], 0, v[6:7]
	v_lshl_add_u64 v[16:17], s[6:7], 0, v[16:17]
	global_load_dwordx4 v[2:5], v[2:3], off
	v_lshl_add_u64 v[16:17], v[16:17], 0, v[6:7]
	global_load_dwordx4 v[12:15], v[12:13], off
	v_lshlrev_b32_e32 v10, 7, v10
	global_load_dwordx4 v[16:19], v[16:17], off
	v_add_u32_e32 v31, 0x20000, v1
	v_add_u32_e32 v38, 0x100000, v8
	v_ashrrev_i32_e32 v39, 5, v31
	v_bfe_u32 v40, v31, 3, 2
	v_mad_i64_i32 v[32:33], s[10:11], v39, 12, 0
	v_or_b32_e32 v32, v32, v40
	v_lshl_add_u64 v[34:35], v[32:33], 2, s[4:5]
	v_lshl_add_u64 v[42:43], v[32:33], 0, 4
	global_load_dword v41, v[34:35], off
	v_lshl_add_u64 v[34:35], v[42:43], 2, s[4:5]
	v_lshl_add_u64 v[46:47], v[32:33], 0, 8
	global_load_dword v50, v[34:35], off
	v_lshl_add_u64 v[34:35], v[46:47], 2, s[4:5]
	global_load_dword v52, v[34:35], off
	v_lshlrev_b64 v[32:33], 7, v[32:33]
	v_and_b32_e32 v34, 56, v38
	v_lshlrev_b64 v[42:43], 7, v[42:43]
	v_lshl_add_u64 v[32:33], s[6:7], 0, v[32:33]
	v_lshlrev_b32_e32 v36, 1, v34
	v_mov_b32_e32 v37, v0
	v_lshl_add_u64 v[42:43], s[6:7], 0, v[42:43]
	v_lshlrev_b64 v[46:47], 7, v[46:47]
	v_lshl_add_u64 v[32:33], v[32:33], 0, v[36:37]
	v_lshl_add_u64 v[42:43], v[42:43], 0, v[36:37]
	v_lshl_add_u64 v[46:47], s[6:7], 0, v[46:47]
	global_load_dwordx4 v[32:35], v[32:33], off
	v_lshl_add_u64 v[46:47], v[46:47], 0, v[36:37]
	global_load_dwordx4 v[42:45], v[42:43], off
	v_lshlrev_b32_e32 v40, 7, v40
	global_load_dwordx4 v[46:49], v[46:47], off
	v_add_u32_e32 v61, 0x40000, v1
	v_add_u32_e32 v68, 0x200000, v8
	v_ashrrev_i32_e32 v69, 5, v61
	v_bfe_u32 v70, v61, 3, 2
	v_mad_i64_i32 v[62:63], s[10:11], v69, 12, 0
	v_or_b32_e32 v62, v62, v70
	v_lshl_add_u64 v[64:65], v[62:63], 2, s[4:5]
	v_lshl_add_u64 v[72:73], v[62:63], 0, 4
	global_load_dword v71, v[64:65], off
	v_lshl_add_u64 v[64:65], v[72:73], 2, s[4:5]
	v_lshl_add_u64 v[76:77], v[62:63], 0, 8
	global_load_dword v80, v[64:65], off
	v_lshl_add_u64 v[64:65], v[76:77], 2, s[4:5]
	global_load_dword v82, v[64:65], off
	v_lshlrev_b64 v[62:63], 7, v[62:63]
	v_and_b32_e32 v64, 56, v68
	v_lshlrev_b64 v[72:73], 7, v[72:73]
	v_lshl_add_u64 v[62:63], s[6:7], 0, v[62:63]
	v_lshlrev_b32_e32 v66, 1, v64
	v_mov_b32_e32 v67, v0
	v_lshl_add_u64 v[72:73], s[6:7], 0, v[72:73]
	v_lshlrev_b64 v[76:77], 7, v[76:77]
	v_lshl_add_u64 v[62:63], v[62:63], 0, v[66:67]
	v_lshl_add_u64 v[72:73], v[72:73], 0, v[66:67]
	v_lshl_add_u64 v[76:77], s[6:7], 0, v[76:77]
	global_load_dwordx4 v[62:65], v[62:63], off
	v_lshl_add_u64 v[76:77], v[76:77], 0, v[66:67]
	global_load_dwordx4 v[72:75], v[72:73], off
	v_lshlrev_b32_e32 v70, 7, v70
	global_load_dwordx4 v[76:79], v[76:77], off
	v_add_u32_e32 v91, 0x60000, v1
	v_add_u32_e32 v98, 0x300000, v8
	v_ashrrev_i32_e32 v99, 5, v91
	v_bfe_u32 v100, v91, 3, 2
	v_mad_i64_i32 v[92:93], s[10:11], v99, 12, 0
	v_or_b32_e32 v92, v92, v100
	v_lshl_add_u64 v[94:95], v[92:93], 2, s[4:5]
	v_lshl_add_u64 v[102:103], v[92:93], 0, 4
	global_load_dword v101, v[94:95], off
	v_lshl_add_u64 v[94:95], v[102:103], 2, s[4:5]
	v_lshl_add_u64 v[106:107], v[92:93], 0, 8
	global_load_dword v110, v[94:95], off
	v_lshl_add_u64 v[94:95], v[106:107], 2, s[4:5]
	global_load_dword v112, v[94:95], off
	v_lshlrev_b64 v[92:93], 7, v[92:93]
	v_and_b32_e32 v94, 56, v98
	v_lshlrev_b64 v[102:103], 7, v[102:103]
	v_lshl_add_u64 v[92:93], s[6:7], 0, v[92:93]
	v_lshlrev_b32_e32 v96, 1, v94
	v_mov_b32_e32 v97, v0
	v_lshl_add_u64 v[102:103], s[6:7], 0, v[102:103]
	v_lshlrev_b64 v[106:107], 7, v[106:107]
	v_lshl_add_u64 v[92:93], v[92:93], 0, v[96:97]
	v_lshl_add_u64 v[102:103], v[102:103], 0, v[96:97]
	v_lshl_add_u64 v[106:107], s[6:7], 0, v[106:107]
	global_load_dwordx4 v[92:95], v[92:93], off
	v_lshl_add_u64 v[106:107], v[106:107], 0, v[96:97]
	global_load_dwordx4 v[102:105], v[102:103], off
	v_lshlrev_b32_e32 v100, 7, v100
	global_load_dwordx4 v[106:109], v[106:107], off
	s_waitcnt vmcnt(21)
	v_max3_f32 v23, v11, v20, v22
	v_sub_f32_e32 v11, v11, v23
	v_exp_f32_e32 v21, v11
	v_sub_f32_e32 v11, v20, v23
	v_exp_f32_e32 v11, v11
	v_sub_f32_e32 v20, v22, v23
	v_exp_f32_e32 v20, v20
	v_add_f32_e32 v22, v21, v11
	v_add_f32_e32 v22, v20, v22
	v_rcp_f32_e32 v22, v22
	s_waitcnt vmcnt(19)
	v_lshlrev_b32_e32 v23, 16, v12
	v_and_b32_e32 v24, 0xffff0000, v12
	v_lshlrev_b32_e32 v25, 16, v13
	v_and_b32_e32 v26, 0xffff0000, v13
	v_pk_mul_f32 v[12:13], v[20:21], v[22:23] op_sel_hi:[1,0]
	v_lshlrev_b32_e32 v21, 16, v2
	s_waitcnt vmcnt(18)
; __device__ __forceinline__ unsigned cvt_pk_bf16(float lo, float hi) { unsigned r; asm volatile("v_cvt_pk_bf16_f32 %0, %1, %2" : "=v"(r) : "v"(lo), "v"(hi)); return r; }
; __device__ __forceinline__ float bf2f(unsigned h) { return __uint_as_float(h << 16); }
; #define LSE ((float*)WSP(WS_A + A_LSE))
; __global__ void __launch_bounds__(512, 2) mega_fwd(KArgs a) {
;     ...
;             for (int e = gw * 64 + lane; e < T_ * 32; e += NGW * 64) {
;                 const int t = e >> 5, h = (e >> 3) & 3, ch = e & 7;
;                 const float l0 = LSE[(size_t)t * 12 + h], l1 = LSE[(size_t)t * 12 + 4 + h], l2 = LSE[(size_t)t * 12 + 8 + h];
;                 const u32x4 a0 = *(const u32x4*)(ODIL + ((size_t)t * 12 + h) * 64 + ch * 8), a1 = *(const u32x4*)(ODIL + ((size_t)t * 12 + 4 + h) * 64 + ch * 8), a2 = *(const u32x4*)(ODIL + ((size_t)t * 12 + 8 + h) * 64 + ch * 8);
;                 const float mx = fmaxf(l0, fmaxf(l1, l2));
;                 float w0 = __builtin_amdgcn_exp2f(l0 - mx), w1 = __builtin_amdgcn_exp2f(l1 - mx), w2 = __builtin_amdgcn_exp2f(l2 - mx);
;                 const float inv = __builtin_amdgcn_rcpf(w0 + w1 + w2); w0 *= inv; w1 *= inv; w2 *= inv;
;                 u32x4 o;
; #pragma unroll
;                 for (int q = 0; q < 4; ++q) {
;                     const float lo = w0 * bf2f(a0[q] & 0xffffu) + w1 * bf2f(a1[q] & 0xffffu) + w2 * bf2f(a2[q] & 0xffffu);
;                     const float hi2 = w0 * bf2f(a0[q] >> 16) + w1 * bf2f(a1[q] >> 16) + w2 * bf2f(a2[q] >> 16);
;                     o[q] = pg8::cvt_pk_bf16(lo, hi2);
;                 }
;                 *(u32x4*)(MIX + (size_t)t * 768 + 512 + h * 64 + ch * 8) = o;
;             }
	v_lshlrev_b32_e32 v20, 16, v16
	v_mul_f32_e32 v11, v11, v22
	v_pk_mul_f32 v[20:21], v[12:13], v[20:21]
	v_lshlrev_b32_e32 v27, 16, v14
	v_fma_f32 v21, v11, v23, v21
	v_add_f32_e32 v22, v20, v21
	v_and_b32_e32 v21, 0xffff0000, v2
	v_and_b32_e32 v20, 0xffff0000, v16
	v_pk_mul_f32 v[20:21], v[12:13], v[20:21]
	v_and_b32_e32 v14, 0xffff0000, v14
	v_fma_f32 v2, v11, v24, v21
	v_add_f32_e32 v2, v20, v2
	v_lshlrev_b32_e32 v21, 16, v3
	v_lshlrev_b32_e32 v20, 16, v17
	v_pk_mul_f32 v[20:21], v[12:13], v[20:21]
	v_cvt_pk_bf16_f32 v2, v22, v2
	v_lshlrev_b32_e32 v28, 16, v15
	v_fma_f32 v16, v11, v25, v21
	v_add_f32_e32 v22, v20, v16
	v_and_b32_e32 v21, 0xffff0000, v3
	v_and_b32_e32 v20, 0xffff0000, v17
	v_pk_mul_f32 v[16:17], v[12:13], v[20:21]
	s_nop 0
	v_fma_f32 v3, v11, v26, v17
	v_add_f32_e32 v3, v16, v3
	v_lshlrev_b32_e32 v17, 16, v4
	v_lshlrev_b32_e32 v16, 16, v18
	v_pk_mul_f32 v[16:17], v[12:13], v[16:17]
	v_cvt_pk_bf16_f32 v3, v22, v3
	s_nop 0
	v_fma_f32 v17, v11, v27, v17
	v_add_f32_e32 v20, v16, v17
	v_and_b32_e32 v17, 0xffff0000, v4
	v_and_b32_e32 v16, 0xffff0000, v18
	v_pk_mul_f32 v[16:17], v[12:13], v[16:17]
	s_nop 0
	v_fma_f32 v4, v11, v14, v17
	v_add_f32_e32 v4, v16, v4
	v_lshlrev_b32_e32 v17, 16, v5
	v_lshlrev_b32_e32 v16, 16, v19
	v_pk_mul_f32 v[16:17], v[12:13], v[16:17]
	v_cvt_pk_bf16_f32 v4, v20, v4
	s_nop 0
	v_fma_f32 v14, v11, v28, v17
	v_add_f32_e32 v16, v16, v14
	v_and_b32_e32 v17, 0xffff0000, v15
	v_and_b32_e32 v15, 0xffff0000, v5
	v_and_b32_e32 v14, 0xffff0000, v19
	v_pk_mul_f32 v[12:13], v[12:13], v[14:15]
	s_nop 0
	v_fma_f32 v5, v11, v17, v13
	v_add_f32_e32 v5, v12, v5
	v_mov_b64_e32 v[12:13], s[2:3]
	v_mad_i64_i32 v[12:13], s[10:11], v9, s30, v[12:13]
	v_mov_b32_e32 v11, v0
	v_lshl_add_u64 v[10:11], v[12:13], 0, v[10:11]
	v_lshl_add_u64 v[6:7], v[10:11], 0, v[6:7]
	v_add_co_u32_e32 v6, vcc, 0x8c00000, v6
	v_cvt_pk_bf16_f32 v5, v16, v5
	s_nop 1
	v_addc_co_u32_e32 v7, vcc, 0, v7, vcc
	global_store_dwordx4 v[6:7], v[2:5], off offset:1024
	s_nop 1
	s_waitcnt vmcnt(16)
	v_max3_f32 v53, v41, v50, v52
	v_sub_f32_e32 v41, v41, v53
	v_exp_f32_e32 v51, v41
	v_sub_f32_e32 v41, v50, v53
	v_exp_f32_e32 v41, v41
	v_sub_f32_e32 v50, v52, v53
	v_exp_f32_e32 v50, v50
	v_add_f32_e32 v52, v51, v41
	v_add_f32_e32 v52, v50, v52
	v_rcp_f32_e32 v52, v52
	s_waitcnt vmcnt(14)
	v_lshlrev_b32_e32 v53, 16, v42
	v_and_b32_e32 v54, 0xffff0000, v42
	v_lshlrev_b32_e32 v55, 16, v43
	v_and_b32_e32 v56, 0xffff0000, v43
	v_pk_mul_f32 v[42:43], v[50:51], v[52:53] op_sel_hi:[1,0]
	v_lshlrev_b32_e32 v51, 16, v32
	s_waitcnt vmcnt(13)
	v_lshlrev_b32_e32 v50, 16, v46
	v_mul_f32_e32 v41, v41, v52
	v_pk_mul_f32 v[50:51], v[42:43], v[50:51]
	v_lshlrev_b32_e32 v57, 16, v44
	v_fma_f32 v51, v41, v53, v51
	v_add_f32_e32 v52, v50, v51
	v_and_b32_e32 v51, 0xffff0000, v32
	v_and_b32_e32 v50, 0xffff0000, v46
	v_pk_mul_f32 v[50:51], v[42:43], v[50:51]
	v_and_b32_e32 v44, 0xffff0000, v44
	v_fma_f32 v32, v41, v54, v51
	v_add_f32_e32 v32, v50, v32
	v_lshlrev_b32_e32 v51, 16, v33
	v_lshlrev_b32_e32 v50, 16, v47
	v_pk_mul_f32 v[50:51], v[42:43], v[50:51]
	v_cvt_pk_bf16_f32 v32, v52, v32
	v_lshlrev_b32_e32 v58, 16, v45
	v_fma_f32 v46, v41, v55, v51
	v_add_f32_e32 v52, v50, v46
	v_and_b32_e32 v51, 0xffff0000, v33
	v_and_b32_e32 v50, 0xffff0000, v47
	v_pk_mul_f32 v[46:47], v[42:43], v[50:51]
	s_nop 0
	v_fma_f32 v33, v41, v56, v47
	v_add_f32_e32 v33, v46, v33
	v_lshlrev_b32_e32 v47, 16, v34
	v_lshlrev_b32_e32 v46, 16, v48
	v_pk_mul_f32 v[46:47], v[42:43], v[46:47]
	v_cvt_pk_bf16_f32 v33, v52, v33
	s_nop 0
	v_fma_f32 v47, v41, v57, v47
	v_add_f32_e32 v50, v46, v47
	v_and_b32_e32 v47, 0xffff0000, v34
	v_and_b32_e32 v46, 0xffff0000, v48
	v_pk_mul_f32 v[46:47], v[42:43], v[46:47]
	s_nop 0
	v_fma_f32 v34, v41, v44, v47
	v_add_f32_e32 v34, v46, v34
	v_lshlrev_b32_e32 v47, 16, v35
	v_lshlrev_b32_e32 v46, 16, v49
	v_pk_mul_f32 v[46:47], v[42:43], v[46:47]
	v_cvt_pk_bf16_f32 v34, v50, v34
	s_nop 0
	v_fma_f32 v44, v41, v58, v47
	v_add_f32_e32 v46, v46, v44
	v_and_b32_e32 v47, 0xffff0000, v45
	v_and_b32_e32 v45, 0xffff0000, v35
	v_and_b32_e32 v44, 0xffff0000, v49
	v_pk_mul_f32 v[42:43], v[42:43], v[44:45]
	s_nop 0
	v_fma_f32 v35, v41, v47, v43
	v_add_f32_e32 v35, v42, v35
	v_mov_b64_e32 v[42:43], s[2:3]
	v_mad_i64_i32 v[42:43], s[10:11], v39, s30, v[42:43]
	v_mov_b32_e32 v41, v0
	v_lshl_add_u64 v[40:41], v[42:43], 0, v[40:41]
	v_lshl_add_u64 v[36:37], v[40:41], 0, v[36:37]
	v_add_co_u32_e32 v36, vcc, 0x8c00000, v36
	v_cvt_pk_bf16_f32 v35, v46, v35
	s_nop 1
	v_addc_co_u32_e32 v37, vcc, 0, v37, vcc
	global_store_dwordx4 v[36:37], v[32:35], off offset:1024
	s_nop 1
	s_waitcnt vmcnt(11)
	v_max3_f32 v83, v71, v80, v82
	v_sub_f32_e32 v71, v71, v83
	v_exp_f32_e32 v81, v71
	v_sub_f32_e32 v71, v80, v83
	v_exp_f32_e32 v71, v71
	v_sub_f32_e32 v80, v82, v83
	v_exp_f32_e32 v80, v80
	v_add_f32_e32 v82, v81, v71
	v_add_f32_e32 v82, v80, v82
	v_rcp_f32_e32 v82, v82
	s_waitcnt vmcnt(9)
; __device__ __forceinline__ unsigned cvt_pk_bf16(float lo, float hi) { unsigned r; asm volatile("v_cvt_pk_bf16_f32 %0, %1, %2" : "=v"(r) : "v"(lo), "v"(hi)); return r; }
; __device__ __forceinline__ float bf2f(unsigned h) { return __uint_as_float(h << 16); }
; #define LSE ((float*)WSP(WS_A + A_LSE))
; __global__ void __launch_bounds__(512, 2) mega_fwd(KArgs a) {
;     ...
;             for (int e = gw * 64 + lane; e < T_ * 32; e += NGW * 64) {
;                 const int t = e >> 5, h = (e >> 3) & 3, ch = e & 7;
;                 const float l0 = LSE[(size_t)t * 12 + h], l1 = LSE[(size_t)t * 12 + 4 + h], l2 = LSE[(size_t)t * 12 + 8 + h];
;                 const u32x4 a0 = *(const u32x4*)(ODIL + ((size_t)t * 12 + h) * 64 + ch * 8), a1 = *(const u32x4*)(ODIL + ((size_t)t * 12 + 4 + h) * 64 + ch * 8), a2 = *(const u32x4*)(ODIL + ((size_t)t * 12 + 8 + h) * 64 + ch * 8);
;                 const float mx = fmaxf(l0, fmaxf(l1, l2));
;                 float w0 = __builtin_amdgcn_exp2f(l0 - mx), w1 = __builtin_amdgcn_exp2f(l1 - mx), w2 = __builtin_amdgcn_exp2f(l2 - mx);
;                 const float inv = __builtin_amdgcn_rcpf(w0 + w1 + w2); w0 *= inv; w1 *= inv; w2 *= inv;
;                 u32x4 o;
; #pragma unroll
;                 for (int q = 0; q < 4; ++q) {
;                     const float lo = w0 * bf2f(a0[q] & 0xffffu) + w1 * bf2f(a1[q] & 0xffffu) + w2 * bf2f(a2[q] & 0xffffu);
;                     const float hi2 = w0 * bf2f(a0[q] >> 16) + w1 * bf2f(a1[q] >> 16) + w2 * bf2f(a2[q] >> 16);
;                     o[q] = pg8::cvt_pk_bf16(lo, hi2);
;                 }
;                 *(u32x4*)(MIX + (size_t)t * 768 + 512 + h * 64 + ch * 8) = o;
;             }
	v_lshlrev_b32_e32 v83, 16, v72
	v_and_b32_e32 v84, 0xffff0000, v72
	v_lshlrev_b32_e32 v85, 16, v73
	v_and_b32_e32 v86, 0xffff0000, v73
	v_pk_mul_f32 v[72:73], v[80:81], v[82:83] op_sel_hi:[1,0]
	v_lshlrev_b32_e32 v81, 16, v62
	s_waitcnt vmcnt(8)
	v_lshlrev_b32_e32 v80, 16, v76
	v_mul_f32_e32 v71, v71, v82
	v_pk_mul_f32 v[80:81], v[72:73], v[80:81]
	v_lshlrev_b32_e32 v87, 16, v74
	v_fma_f32 v81, v71, v83, v81
	v_add_f32_e32 v82, v80, v81
	v_and_b32_e32 v81, 0xffff0000, v62
	v_and_b32_e32 v80, 0xffff0000, v76
	v_pk_mul_f32 v[80:81], v[72:73], v[80:81]
	v_and_b32_e32 v74, 0xffff0000, v74
	v_fma_f32 v62, v71, v84, v81
	v_add_f32_e32 v62, v80, v62
	v_lshlrev_b32_e32 v81, 16, v63
	v_lshlrev_b32_e32 v80, 16, v77
	v_pk_mul_f32 v[80:81], v[72:73], v[80:81]
	v_cvt_pk_bf16_f32 v62, v82, v62
	v_lshlrev_b32_e32 v88, 16, v75
	v_fma_f32 v76, v71, v85, v81
	v_add_f32_e32 v82, v80, v76
	v_and_b32_e32 v81, 0xffff0000, v63
	v_and_b32_e32 v80, 0xffff0000, v77
	v_pk_mul_f32 v[76:77], v[72:73], v[80:81]
	s_nop 0
	v_fma_f32 v63, v71, v86, v77
	v_add_f32_e32 v63, v76, v63
	v_lshlrev_b32_e32 v77, 16, v64
	v_lshlrev_b32_e32 v76, 16, v78
	v_pk_mul_f32 v[76:77], v[72:73], v[76:77]
	v_cvt_pk_bf16_f32 v63, v82, v63
	s_nop 0
	v_fma_f32 v77, v71, v87, v77
	v_add_f32_e32 v80, v76, v77
	v_and_b32_e32 v77, 0xffff0000, v64
	v_and_b32_e32 v76, 0xffff0000, v78
	v_pk_mul_f32 v[76:77], v[72:73], v[76:77]
	s_nop 0
	v_fma_f32 v64, v71, v74, v77
	v_add_f32_e32 v64, v76, v64
	v_lshlrev_b32_e32 v77, 16, v65
	v_lshlrev_b32_e32 v76, 16, v79
	v_pk_mul_f32 v[76:77], v[72:73], v[76:77]
	v_cvt_pk_bf16_f32 v64, v80, v64
	s_nop 0
	v_fma_f32 v74, v71, v88, v77
	v_add_f32_e32 v76, v76, v74
	v_and_b32_e32 v77, 0xffff0000, v75
	v_and_b32_e32 v75, 0xffff0000, v65
	v_and_b32_e32 v74, 0xffff0000, v79
	v_pk_mul_f32 v[72:73], v[72:73], v[74:75]
	s_nop 0
	v_fma_f32 v65, v71, v77, v73
	v_add_f32_e32 v65, v72, v65
	v_mov_b64_e32 v[72:73], s[2:3]
	v_mad_i64_i32 v[72:73], s[10:11], v69, s30, v[72:73]
	v_mov_b32_e32 v71, v0
	v_lshl_add_u64 v[70:71], v[72:73], 0, v[70:71]
	v_lshl_add_u64 v[66:67], v[70:71], 0, v[66:67]
	v_add_co_u32_e32 v66, vcc, 0x8c00000, v66
	v_cvt_pk_bf16_f32 v65, v76, v65
	s_nop 1
	v_addc_co_u32_e32 v67, vcc, 0, v67, vcc
	global_store_dwordx4 v[66:67], v[62:65], off offset:1024
	s_nop 1
	s_waitcnt vmcnt(6)
	v_max3_f32 v113, v101, v110, v112
	v_sub_f32_e32 v101, v101, v113
	v_exp_f32_e32 v111, v101
	v_sub_f32_e32 v101, v110, v113
	v_exp_f32_e32 v101, v101
	v_sub_f32_e32 v110, v112, v113
	v_exp_f32_e32 v110, v110
	v_add_f32_e32 v112, v111, v101
	v_add_f32_e32 v112, v110, v112
	v_rcp_f32_e32 v112, v112
	s_waitcnt vmcnt(4)
	v_lshlrev_b32_e32 v113, 16, v102
	v_and_b32_e32 v114, 0xffff0000, v102
	v_lshlrev_b32_e32 v115, 16, v103
	v_and_b32_e32 v116, 0xffff0000, v103
	v_pk_mul_f32 v[102:103], v[110:111], v[112:113] op_sel_hi:[1,0]
	v_lshlrev_b32_e32 v111, 16, v92
	s_waitcnt vmcnt(3)
	v_lshlrev_b32_e32 v110, 16, v106
	v_mul_f32_e32 v101, v101, v112
	v_pk_mul_f32 v[110:111], v[102:103], v[110:111]
	v_lshlrev_b32_e32 v117, 16, v104
	v_fma_f32 v111, v101, v113, v111
	v_add_f32_e32 v112, v110, v111
	v_and_b32_e32 v111, 0xffff0000, v92
	v_and_b32_e32 v110, 0xffff0000, v106
	v_pk_mul_f32 v[110:111], v[102:103], v[110:111]
	v_and_b32_e32 v104, 0xffff0000, v104
	v_fma_f32 v92, v101, v114, v111
	v_add_f32_e32 v92, v110, v92
	v_lshlrev_b32_e32 v111, 16, v93
	v_lshlrev_b32_e32 v110, 16, v107
	v_pk_mul_f32 v[110:111], v[102:103], v[110:111]
	v_cvt_pk_bf16_f32 v92, v112, v92
	v_lshlrev_b32_e32 v118, 16, v105
	v_fma_f32 v106, v101, v115, v111
	v_add_f32_e32 v112, v110, v106
	v_and_b32_e32 v111, 0xffff0000, v93
	v_and_b32_e32 v110, 0xffff0000, v107
	v_pk_mul_f32 v[106:107], v[102:103], v[110:111]
	s_nop 0
	v_fma_f32 v93, v101, v116, v107
	v_add_f32_e32 v93, v106, v93
	v_lshlrev_b32_e32 v107, 16, v94
	v_lshlrev_b32_e32 v106, 16, v108
	v_pk_mul_f32 v[106:107], v[102:103], v[106:107]
	v_cvt_pk_bf16_f32 v93, v112, v93
	s_nop 0
	v_fma_f32 v107, v101, v117, v107
	v_add_f32_e32 v110, v106, v107
	v_and_b32_e32 v107, 0xffff0000, v94
	v_and_b32_e32 v106, 0xffff0000, v108
	v_pk_mul_f32 v[106:107], v[102:103], v[106:107]
	s_nop 0
	v_fma_f32 v94, v101, v104, v107
	v_add_f32_e32 v94, v106, v94
	v_lshlrev_b32_e32 v107, 16, v95
	v_lshlrev_b32_e32 v106, 16, v109
	v_pk_mul_f32 v[106:107], v[102:103], v[106:107]
	v_cvt_pk_bf16_f32 v94, v110, v94
	s_nop 0
	v_fma_f32 v104, v101, v118, v107
	v_add_f32_e32 v106, v106, v104
	v_and_b32_e32 v107, 0xffff0000, v105
	v_and_b32_e32 v105, 0xffff0000, v95
	v_and_b32_e32 v104, 0xffff0000, v109
	v_pk_mul_f32 v[102:103], v[102:103], v[104:105]
	s_nop 0
	v_fma_f32 v95, v101, v107, v103
	v_add_f32_e32 v95, v102, v95
	v_mov_b64_e32 v[102:103], s[2:3]
	v_mad_i64_i32 v[102:103], s[10:11], v99, s30, v[102:103]
	v_mov_b32_e32 v101, v0
	v_lshl_add_u64 v[100:101], v[102:103], 0, v[100:101]
	v_lshl_add_u64 v[96:97], v[100:101], 0, v[96:97]
	v_add_co_u32_e32 v96, vcc, 0x8c00000, v96
	v_cvt_pk_bf16_f32 v95, v106, v95
	s_nop 1
	v_addc_co_u32_e32 v97, vcc, 0, v97, vcc
	global_store_dwordx4 v[96:97], v[92:95], off offset:1024
	s_nop 1
